# phase C V-transposed output: 4x4 lane-quad transpose (DPP) turns four 2-byte stores per fragment into one 8-byte store
# speedup vs baseline: 1.0074x; 1.0006x over previous
.LBB0_268:
	v_and_b32_e32 v232, 1, v204
	v_and_b32_e32 v233, 2, v204
	v_and_b32_e32 v230, 3, v204
	v_mul_u32_u24_e32 v230, 0x3ffe, v230
	v_mov_b32_e32 v231, v189
	s_cmpk_gt_i32 s10, 0x2ff
	s_cselect_b64 s[2:3], -1, 0
	s_add_i32 s0, s10, 0xfffffd00
	s_cmpk_lt_i32 s10, 0x300
	s_cselect_b32 s4, 24, 32
	v_cvt_f32_ubyte0_e32 v0, s4
	v_rcp_iflag_f32_e32 v0, v0
	s_movk_i32 s11, 0x180
	s_cselect_b32 s5, s10, s0
	s_cselect_b32 s0, 0, 0x300
	v_mul_f32_e32 v0, 0x4f7ffffe, v0
	v_cvt_u32_f32_e32 v0, v0
	s_cselect_b32 s13, s11, 0x80
	s_sub_i32 s14, 0, s4
	s_abs_i32 s12, s5
	v_readfirstlane_b32 s15, v0
	s_mul_i32 s14, s14, s15
	s_mul_hi_u32 s14, s15, s14
	s_add_i32 s15, s15, s14
	s_mul_hi_u32 s14, s12, s15
	s_mul_i32 s15, s14, s4
	s_sub_i32 s12, s12, s15
	s_ashr_i32 s11, s5, 31
	s_add_i32 s15, s14, 1
	s_sub_i32 s16, s12, s4
	s_cmp_ge_u32 s12, s4
	s_cselect_b32 s14, s15, s14
	s_cselect_b32 s12, s16, s12
	s_add_i32 s15, s14, 1
	s_cmp_ge_u32 s12, s4
	s_cselect_b32 s12, s15, s14
	s_xor_b32 s12, s12, s11
	s_sub_i32 s11, s12, s11
	s_mul_i32 s4, s11, s4
	s_sub_i32 s4, s5, s4
	s_bfe_i32 s5, s4, 0x80000
	s_bfe_u32 s5, s5, 0x2000d
	s_add_i32 s5, s4, s5
	s_bfe_i32 s12, s5, 0x80000
	s_and_b32 s5, s5, 0xfc
	s_sub_i32 s4, s4, s5
	s_sext_i32_i8 s4, s4
	s_lshl_b32 s5, s11, 10
	s_lshl_b32 s11, s4, 8
	s_add_i32 s11, s11, s5
	v_ashrrev_i32_e32 v2, 1, v42
	v_add_u32_e32 v4, s11, v2
	v_mov_b64_e32 v[0:1], s[88:89]
	v_mad_i64_i32 v[0:1], s[4:5], v4, s84, v[0:1]
	v_and_b32_e32 v3, 1, v42
	v_lshl_add_u64 v[0:1], v[0:1], 0, s[0:1]
	s_lshr_b32 s0, s13, 1
	v_mul_u32_u24_e32 v4, s0, v3
	s_sext_i32_i16 s12, s12
	v_lshlrev_b32_e32 v188, 1, v4
	s_lshr_b32 s12, s12, 2
	v_lshl_add_u64 v[0:1], v[0:1], 0, v[188:189]
	s_lshr_b32 s0, s13, 4
	v_mov_b32_e32 v4, 0
	global_load_dwordx4 v[12:15], v[0:1], off
	global_load_dwordx4 v[16:19], v[0:1], off offset:16
	global_load_dwordx4 v[20:23], v[0:1], off offset:32
	global_load_dwordx4 v[24:27], v[0:1], off offset:48
	global_load_dwordx4 v[28:31], v[0:1], off offset:64
	global_load_dwordx4 v[32:35], v[0:1], off offset:80
	global_load_dwordx4 v[36:39], v[0:1], off offset:96
	global_load_dwordx4 v[40:43], v[0:1], off offset:112
	s_cmp_lt_u32 s0, 9
	s_cbranch_scc1 .Lcst_ld8
	global_load_dwordx4 v[44:47], v[0:1], off offset:128
	global_load_dwordx4 v[48:51], v[0:1], off offset:144
	global_load_dwordx4 v[52:55], v[0:1], off offset:160
	global_load_dwordx4 v[56:59], v[0:1], off offset:176
	global_load_dwordx4 v[60:63], v[0:1], off offset:192
	global_load_dwordx4 v[64:67], v[0:1], off offset:208
	global_load_dwordx4 v[68:71], v[0:1], off offset:224
	global_load_dwordx4 v[72:75], v[0:1], off offset:240
	global_load_dwordx4 v[76:79], v[0:1], off offset:256
	global_load_dwordx4 v[80:83], v[0:1], off offset:272
	global_load_dwordx4 v[84:87], v[0:1], off offset:288
	global_load_dwordx4 v[88:91], v[0:1], off offset:304
	global_load_dwordx4 v[92:95], v[0:1], off offset:320
	global_load_dwordx4 v[96:99], v[0:1], off offset:336
	global_load_dwordx4 v[100:103], v[0:1], off offset:352
	global_load_dwordx4 v[104:107], v[0:1], off offset:368

.LBB0_312:
	v_readlane_b32 s12, v252, 58
	v_lshlrev_b64 v[74:75], 20, v[64:65]
	v_readlane_b32 s13, v252, 59
	v_mov_b32_e32 v67, v189
	v_mov_b32_e32 v71, v189
	v_lshl_add_u64 v[74:75], s[12:13], 0, v[74:75]
	v_lshl_add_u64 v[74:75], v[74:75], 0, v[66:67]
	v_lshl_add_u64 v[74:75], v[74:75], 0, v[70:71]
	s_waitcnt lgkmcnt(0)
	v_mul_f32_e32 v236, v60, v68
	v_mul_f32_e32 v237, v61, v68
	v_mul_f32_e32 v238, v62, v68
	v_mul_f32_e32 v239, v63, v68
	v_cmp_ne_u32_e32 vcc, 0, v232
	s_nop 1
	v_cndmask_b32_e32 v240, v237, v236, vcc
	v_cndmask_b32_e32 v241, v239, v238, vcc
	s_nop 1
	v_mov_b32_dpp v242, v240 quad_perm:[1,0,3,2] row_mask:0xf bank_mask:0xf
	v_mov_b32_dpp v243, v241 quad_perm:[1,0,3,2] row_mask:0xf bank_mask:0xf
	s_nop 1
	v_cndmask_b32_e32 v236, v236, v242, vcc
	v_cndmask_b32_e32 v237, v242, v237, vcc
	v_cndmask_b32_e32 v238, v238, v243, vcc
	v_cndmask_b32_e32 v239, v243, v239, vcc
	v_cmp_ne_u32_e32 vcc, 0, v233
	s_nop 1
	v_cndmask_b32_e32 v240, v238, v236, vcc
	v_cndmask_b32_e32 v241, v239, v237, vcc
	s_nop 1
	v_mov_b32_dpp v242, v240 quad_perm:[2,3,0,1] row_mask:0xf bank_mask:0xf
	v_mov_b32_dpp v243, v241 quad_perm:[2,3,0,1] row_mask:0xf bank_mask:0xf
	s_nop 1
	v_cndmask_b32_e32 v236, v236, v242, vcc
	v_cndmask_b32_e32 v238, v242, v238, vcc
	v_cndmask_b32_e32 v237, v237, v243, vcc
	v_cndmask_b32_e32 v239, v243, v239, vcc
	v_cvt_pk_bf16_f32 v244, v236, v237
	v_cvt_pk_bf16_f32 v245, v238, v239
	v_add_co_u32_e32 v234, vcc, 0xfff00000, v74
	s_nop 1
	v_addc_co_u32_e32 v235, vcc, -1, v75, vcc
	v_lshl_add_u64 v[234:235], v[234:235], 0, v[230:231]
	global_store_dwordx2 v[234:235], v[244:245], off
	s_nop 1
	s_or_saveexec_b64 s[2:3], s[2:3]
	v_lshlrev_b32_e32 v188, 1, v73
	s_xor_b64 exec, exec, s[2:3]
	s_cbranch_execz .LBB0_275

.LBB0_314:
	v_readlane_b32 s12, v252, 58
	v_lshlrev_b64 v[60:61], 20, v[64:65]
	v_readlane_b32 s13, v252, 59
	v_mov_b32_e32 v67, v189
	v_mov_b32_e32 v71, v189
	v_lshl_add_u64 v[60:61], s[12:13], 0, v[60:61]
	v_lshl_add_u64 v[60:61], v[60:61], 0, v[66:67]
	v_lshl_add_u64 v[60:61], v[60:61], 0, v[70:71]
	s_waitcnt lgkmcnt(0)
	v_mul_f32_e32 v236, v56, v68
	v_mul_f32_e32 v237, v57, v68
	v_mul_f32_e32 v238, v58, v68
	v_mul_f32_e32 v239, v59, v68
	v_cmp_ne_u32_e32 vcc, 0, v232
	s_nop 1
	v_cndmask_b32_e32 v240, v237, v236, vcc
	v_cndmask_b32_e32 v241, v239, v238, vcc
	s_nop 1
	v_mov_b32_dpp v242, v240 quad_perm:[1,0,3,2] row_mask:0xf bank_mask:0xf
	v_mov_b32_dpp v243, v241 quad_perm:[1,0,3,2] row_mask:0xf bank_mask:0xf
	s_nop 1
	v_cndmask_b32_e32 v236, v236, v242, vcc
	v_cndmask_b32_e32 v237, v242, v237, vcc
	v_cndmask_b32_e32 v238, v238, v243, vcc
	v_cndmask_b32_e32 v239, v243, v239, vcc
	v_cmp_ne_u32_e32 vcc, 0, v233
	s_nop 1
	v_cndmask_b32_e32 v240, v238, v236, vcc
	v_cndmask_b32_e32 v241, v239, v237, vcc
	s_nop 1
	v_mov_b32_dpp v242, v240 quad_perm:[2,3,0,1] row_mask:0xf bank_mask:0xf
	v_mov_b32_dpp v243, v241 quad_perm:[2,3,0,1] row_mask:0xf bank_mask:0xf
	s_nop 1
	v_cndmask_b32_e32 v236, v236, v242, vcc
	v_cndmask_b32_e32 v238, v242, v238, vcc
	v_cndmask_b32_e32 v237, v237, v243, vcc
	v_cndmask_b32_e32 v239, v243, v239, vcc
	v_cvt_pk_bf16_f32 v244, v236, v237
	v_cvt_pk_bf16_f32 v245, v238, v239
	v_add_co_u32_e32 v234, vcc, 0xfff40000, v60
	s_nop 1
	v_addc_co_u32_e32 v235, vcc, -1, v61, vcc
	v_lshl_add_u64 v[234:235], v[234:235], 0, v[230:231]
	global_store_dwordx2 v[234:235], v[244:245], off
	s_nop 1
	s_andn2_saveexec_b64 s[2:3], s[2:3]
	s_cbranch_execz .LBB0_277

.LBB0_316:
	v_readlane_b32 s12, v252, 58
	v_lshlrev_b64 v[56:57], 20, v[64:65]
	v_readlane_b32 s13, v252, 59
	v_mov_b32_e32 v67, v189
	v_mov_b32_e32 v71, v189
	v_lshl_add_u64 v[56:57], s[12:13], 0, v[56:57]
	v_lshl_add_u64 v[56:57], v[56:57], 0, v[66:67]
	v_lshl_add_u64 v[56:57], v[56:57], 0, v[70:71]
	s_waitcnt lgkmcnt(0)
	v_mul_f32_e32 v236, v52, v68
	v_mul_f32_e32 v237, v53, v68
	v_mul_f32_e32 v238, v54, v68
	v_mul_f32_e32 v239, v55, v68
	v_cmp_ne_u32_e32 vcc, 0, v232
	s_nop 1
	v_cndmask_b32_e32 v240, v237, v236, vcc
	v_cndmask_b32_e32 v241, v239, v238, vcc
	s_nop 1
	v_mov_b32_dpp v242, v240 quad_perm:[1,0,3,2] row_mask:0xf bank_mask:0xf
	v_mov_b32_dpp v243, v241 quad_perm:[1,0,3,2] row_mask:0xf bank_mask:0xf
	s_nop 1
	v_cndmask_b32_e32 v236, v236, v242, vcc
	v_cndmask_b32_e32 v237, v242, v237, vcc
	v_cndmask_b32_e32 v238, v238, v243, vcc
	v_cndmask_b32_e32 v239, v243, v239, vcc
	v_cmp_ne_u32_e32 vcc, 0, v233
	s_nop 1
	v_cndmask_b32_e32 v240, v238, v236, vcc
	v_cndmask_b32_e32 v241, v239, v237, vcc
	s_nop 1
	v_mov_b32_dpp v242, v240 quad_perm:[2,3,0,1] row_mask:0xf bank_mask:0xf
	v_mov_b32_dpp v243, v241 quad_perm:[2,3,0,1] row_mask:0xf bank_mask:0xf
	s_nop 1
	v_cndmask_b32_e32 v236, v236, v242, vcc
	v_cndmask_b32_e32 v238, v242, v238, vcc
	v_cndmask_b32_e32 v237, v237, v243, vcc
	v_cndmask_b32_e32 v239, v243, v239, vcc
	v_cvt_pk_bf16_f32 v244, v236, v237
	v_cvt_pk_bf16_f32 v245, v238, v239
	v_add_co_u32_e32 v234, vcc, 0xfff80000, v56
	s_nop 1
	v_addc_co_u32_e32 v235, vcc, -1, v57, vcc
	v_lshl_add_u64 v[234:235], v[234:235], 0, v[230:231]
	global_store_dwordx2 v[234:235], v[244:245], off
	s_nop 1
	s_andn2_saveexec_b64 s[2:3], s[2:3]
	s_cbranch_execz .LBB0_279

.LBB0_318:
	v_readlane_b32 s12, v252, 58
	v_lshlrev_b64 v[52:53], 20, v[64:65]
	v_readlane_b32 s13, v252, 59
	v_mov_b32_e32 v67, v189
	v_mov_b32_e32 v71, v189
	v_lshl_add_u64 v[52:53], s[12:13], 0, v[52:53]
	v_lshl_add_u64 v[52:53], v[52:53], 0, v[66:67]
	v_lshl_add_u64 v[52:53], v[52:53], 0, v[70:71]
	s_waitcnt lgkmcnt(0)
	v_mul_f32_e32 v236, v48, v68
	v_mul_f32_e32 v237, v49, v68
	v_mul_f32_e32 v238, v50, v68
	v_mul_f32_e32 v239, v51, v68
	v_cmp_ne_u32_e32 vcc, 0, v232
	s_nop 1
	v_cndmask_b32_e32 v240, v237, v236, vcc
	v_cndmask_b32_e32 v241, v239, v238, vcc
	s_nop 1
	v_mov_b32_dpp v242, v240 quad_perm:[1,0,3,2] row_mask:0xf bank_mask:0xf
	v_mov_b32_dpp v243, v241 quad_perm:[1,0,3,2] row_mask:0xf bank_mask:0xf
	s_nop 1
	v_cndmask_b32_e32 v236, v236, v242, vcc
	v_cndmask_b32_e32 v237, v242, v237, vcc
	v_cndmask_b32_e32 v238, v238, v243, vcc
	v_cndmask_b32_e32 v239, v243, v239, vcc
	v_cmp_ne_u32_e32 vcc, 0, v233
	s_nop 1
	v_cndmask_b32_e32 v240, v238, v236, vcc
	v_cndmask_b32_e32 v241, v239, v237, vcc
	s_nop 1
	v_mov_b32_dpp v242, v240 quad_perm:[2,3,0,1] row_mask:0xf bank_mask:0xf
	v_mov_b32_dpp v243, v241 quad_perm:[2,3,0,1] row_mask:0xf bank_mask:0xf
	s_nop 1
	v_cndmask_b32_e32 v236, v236, v242, vcc
	v_cndmask_b32_e32 v238, v242, v238, vcc
	v_cndmask_b32_e32 v237, v237, v243, vcc
	v_cndmask_b32_e32 v239, v243, v239, vcc
	v_cvt_pk_bf16_f32 v244, v236, v237
	v_cvt_pk_bf16_f32 v245, v238, v239
	v_add_co_u32_e32 v234, vcc, 0xfffc0000, v52
	s_nop 1
	v_addc_co_u32_e32 v235, vcc, -1, v53, vcc
	v_lshl_add_u64 v[234:235], v[234:235], 0, v[230:231]
	global_store_dwordx2 v[234:235], v[244:245], off
	s_nop 1
	s_andn2_saveexec_b64 s[2:3], s[2:3]
	s_cbranch_execnz .LBB0_281
	s_branch .LBB0_282
.LBB0_319:
	v_readlane_b32 s12, v252, 58
	v_lshlrev_b64 v[52:53], 20, v[64:65]
	v_readlane_b32 s13, v252, 59
	v_mov_b32_e32 v67, v189
	v_mov_b32_e32 v51, v189
	v_lshl_add_u64 v[52:53], s[12:13], 0, v[52:53]
	v_lshl_add_u64 v[52:53], v[52:53], 0, v[66:67]
	v_lshl_add_u64 v[52:53], v[52:53], 0, v[50:51]
	s_waitcnt lgkmcnt(0)
	v_mul_f32_e32 v236, v44, v48
	v_mul_f32_e32 v237, v45, v48
	v_mul_f32_e32 v238, v46, v48
	v_mul_f32_e32 v239, v47, v48
	v_cmp_ne_u32_e32 vcc, 0, v232
	s_nop 1
	v_cndmask_b32_e32 v240, v237, v236, vcc
	v_cndmask_b32_e32 v241, v239, v238, vcc
	s_nop 1
	v_mov_b32_dpp v242, v240 quad_perm:[1,0,3,2] row_mask:0xf bank_mask:0xf
	v_mov_b32_dpp v243, v241 quad_perm:[1,0,3,2] row_mask:0xf bank_mask:0xf
	s_nop 1
	v_cndmask_b32_e32 v236, v236, v242, vcc
	v_cndmask_b32_e32 v237, v242, v237, vcc
	v_cndmask_b32_e32 v238, v238, v243, vcc
	v_cndmask_b32_e32 v239, v243, v239, vcc
	v_cmp_ne_u32_e32 vcc, 0, v233
	s_nop 1
	v_cndmask_b32_e32 v240, v238, v236, vcc
	v_cndmask_b32_e32 v241, v239, v237, vcc
	s_nop 1
	v_mov_b32_dpp v242, v240 quad_perm:[2,3,0,1] row_mask:0xf bank_mask:0xf
	v_mov_b32_dpp v243, v241 quad_perm:[2,3,0,1] row_mask:0xf bank_mask:0xf
	s_nop 1
	v_cndmask_b32_e32 v236, v236, v242, vcc
	v_cndmask_b32_e32 v238, v242, v238, vcc
	v_cndmask_b32_e32 v237, v237, v243, vcc
	v_cndmask_b32_e32 v239, v243, v239, vcc
	v_cvt_pk_bf16_f32 v244, v236, v237
	v_cvt_pk_bf16_f32 v245, v238, v239
	v_add_co_u32_e32 v234, vcc, 0xfff00000, v52
	s_nop 1
	v_addc_co_u32_e32 v235, vcc, -1, v53, vcc
	v_lshl_add_u64 v[234:235], v[234:235], 0, v[230:231]
	global_store_dwordx2 v[234:235], v[244:245], off
	s_nop 1
	s_andn2_saveexec_b64 s[2:3], s[2:3]
	s_cbranch_execz .LBB0_284

.LBB0_321:
	v_readlane_b32 s12, v252, 58
	v_lshlrev_b64 v[44:45], 20, v[64:65]
	v_readlane_b32 s13, v252, 59
	v_mov_b32_e32 v67, v189
	v_mov_b32_e32 v51, v189
	v_lshl_add_u64 v[44:45], s[12:13], 0, v[44:45]
	v_lshl_add_u64 v[44:45], v[44:45], 0, v[66:67]
	v_lshl_add_u64 v[44:45], v[44:45], 0, v[50:51]
	s_waitcnt lgkmcnt(0)
	v_mul_f32_e32 v236, v40, v48
	v_mul_f32_e32 v237, v41, v48
	v_mul_f32_e32 v238, v42, v48
	v_mul_f32_e32 v239, v43, v48
	v_cmp_ne_u32_e32 vcc, 0, v232
	s_nop 1
	v_cndmask_b32_e32 v240, v237, v236, vcc
	v_cndmask_b32_e32 v241, v239, v238, vcc
	s_nop 1
	v_mov_b32_dpp v242, v240 quad_perm:[1,0,3,2] row_mask:0xf bank_mask:0xf
	v_mov_b32_dpp v243, v241 quad_perm:[1,0,3,2] row_mask:0xf bank_mask:0xf
	s_nop 1
	v_cndmask_b32_e32 v236, v236, v242, vcc
	v_cndmask_b32_e32 v237, v242, v237, vcc
	v_cndmask_b32_e32 v238, v238, v243, vcc
	v_cndmask_b32_e32 v239, v243, v239, vcc
	v_cmp_ne_u32_e32 vcc, 0, v233
	s_nop 1
	v_cndmask_b32_e32 v240, v238, v236, vcc
	v_cndmask_b32_e32 v241, v239, v237, vcc
	s_nop 1
	v_mov_b32_dpp v242, v240 quad_perm:[2,3,0,1] row_mask:0xf bank_mask:0xf
	v_mov_b32_dpp v243, v241 quad_perm:[2,3,0,1] row_mask:0xf bank_mask:0xf
	s_nop 1
	v_cndmask_b32_e32 v236, v236, v242, vcc
	v_cndmask_b32_e32 v238, v242, v238, vcc
	v_cndmask_b32_e32 v237, v237, v243, vcc
	v_cndmask_b32_e32 v239, v243, v239, vcc
	v_cvt_pk_bf16_f32 v244, v236, v237
	v_cvt_pk_bf16_f32 v245, v238, v239
	v_add_co_u32_e32 v234, vcc, 0xfff40000, v44
	s_nop 1
	v_addc_co_u32_e32 v235, vcc, -1, v45, vcc
	v_lshl_add_u64 v[234:235], v[234:235], 0, v[230:231]
	global_store_dwordx2 v[234:235], v[244:245], off
	s_nop 1
	s_andn2_saveexec_b64 s[2:3], s[2:3]
	s_cbranch_execz .LBB0_286

.LBB0_323:
	v_readlane_b32 s12, v252, 58
	v_lshlrev_b64 v[40:41], 20, v[64:65]
	v_readlane_b32 s13, v252, 59
	v_mov_b32_e32 v67, v189
	v_mov_b32_e32 v51, v189
	v_lshl_add_u64 v[40:41], s[12:13], 0, v[40:41]
	v_lshl_add_u64 v[40:41], v[40:41], 0, v[66:67]
	v_lshl_add_u64 v[40:41], v[40:41], 0, v[50:51]
	s_waitcnt lgkmcnt(0)
	v_mul_f32_e32 v236, v36, v48
	v_mul_f32_e32 v237, v37, v48
	v_mul_f32_e32 v238, v38, v48
	v_mul_f32_e32 v239, v39, v48
	v_cmp_ne_u32_e32 vcc, 0, v232
	s_nop 1
	v_cndmask_b32_e32 v240, v237, v236, vcc
	v_cndmask_b32_e32 v241, v239, v238, vcc
	s_nop 1
	v_mov_b32_dpp v242, v240 quad_perm:[1,0,3,2] row_mask:0xf bank_mask:0xf
	v_mov_b32_dpp v243, v241 quad_perm:[1,0,3,2] row_mask:0xf bank_mask:0xf
	s_nop 1
	v_cndmask_b32_e32 v236, v236, v242, vcc
	v_cndmask_b32_e32 v237, v242, v237, vcc
	v_cndmask_b32_e32 v238, v238, v243, vcc
	v_cndmask_b32_e32 v239, v243, v239, vcc
	v_cmp_ne_u32_e32 vcc, 0, v233
	s_nop 1
	v_cndmask_b32_e32 v240, v238, v236, vcc
	v_cndmask_b32_e32 v241, v239, v237, vcc
	s_nop 1
	v_mov_b32_dpp v242, v240 quad_perm:[2,3,0,1] row_mask:0xf bank_mask:0xf
	v_mov_b32_dpp v243, v241 quad_perm:[2,3,0,1] row_mask:0xf bank_mask:0xf
	s_nop 1
	v_cndmask_b32_e32 v236, v236, v242, vcc
	v_cndmask_b32_e32 v238, v242, v238, vcc
	v_cndmask_b32_e32 v237, v237, v243, vcc
	v_cndmask_b32_e32 v239, v243, v239, vcc
	v_cvt_pk_bf16_f32 v244, v236, v237
	v_cvt_pk_bf16_f32 v245, v238, v239
	v_add_co_u32_e32 v234, vcc, 0xfff80000, v40
	s_nop 1
	v_addc_co_u32_e32 v235, vcc, -1, v41, vcc
	v_lshl_add_u64 v[234:235], v[234:235], 0, v[230:231]
	global_store_dwordx2 v[234:235], v[244:245], off
	s_nop 1
	s_andn2_saveexec_b64 s[2:3], s[2:3]
	s_cbranch_execz .LBB0_288

.LBB0_325:
	v_readlane_b32 s12, v252, 58
	v_lshlrev_b64 v[36:37], 20, v[64:65]
	v_readlane_b32 s13, v252, 59
	v_mov_b32_e32 v67, v189
	v_mov_b32_e32 v51, v189
	v_lshl_add_u64 v[36:37], s[12:13], 0, v[36:37]
	v_lshl_add_u64 v[36:37], v[36:37], 0, v[66:67]
	v_lshl_add_u64 v[36:37], v[36:37], 0, v[50:51]
	s_waitcnt lgkmcnt(0)
	v_mul_f32_e32 v236, v32, v48
	v_mul_f32_e32 v237, v33, v48
	v_mul_f32_e32 v238, v34, v48
	v_mul_f32_e32 v239, v35, v48
	v_cmp_ne_u32_e32 vcc, 0, v232
	s_nop 1
	v_cndmask_b32_e32 v240, v237, v236, vcc
	v_cndmask_b32_e32 v241, v239, v238, vcc
	s_nop 1
	v_mov_b32_dpp v242, v240 quad_perm:[1,0,3,2] row_mask:0xf bank_mask:0xf
	v_mov_b32_dpp v243, v241 quad_perm:[1,0,3,2] row_mask:0xf bank_mask:0xf
	s_nop 1
	v_cndmask_b32_e32 v236, v236, v242, vcc
	v_cndmask_b32_e32 v237, v242, v237, vcc
	v_cndmask_b32_e32 v238, v238, v243, vcc
	v_cndmask_b32_e32 v239, v243, v239, vcc
	v_cmp_ne_u32_e32 vcc, 0, v233
	s_nop 1
	v_cndmask_b32_e32 v240, v238, v236, vcc
	v_cndmask_b32_e32 v241, v239, v237, vcc
	s_nop 1
	v_mov_b32_dpp v242, v240 quad_perm:[2,3,0,1] row_mask:0xf bank_mask:0xf
	v_mov_b32_dpp v243, v241 quad_perm:[2,3,0,1] row_mask:0xf bank_mask:0xf
	s_nop 1
	v_cndmask_b32_e32 v236, v236, v242, vcc
	v_cndmask_b32_e32 v238, v242, v238, vcc
	v_cndmask_b32_e32 v237, v237, v243, vcc
	v_cndmask_b32_e32 v239, v243, v239, vcc
	v_cvt_pk_bf16_f32 v244, v236, v237
	v_cvt_pk_bf16_f32 v245, v238, v239
	v_add_co_u32_e32 v234, vcc, 0xfffc0000, v36
	s_nop 1
	v_addc_co_u32_e32 v235, vcc, -1, v37, vcc
	v_lshl_add_u64 v[234:235], v[234:235], 0, v[230:231]
	global_store_dwordx2 v[234:235], v[244:245], off
	s_nop 1
	s_andn2_saveexec_b64 s[2:3], s[2:3]
	s_cbranch_execnz .LBB0_290
	s_branch .LBB0_291
.LBB0_326:
	v_readlane_b32 s12, v252, 58
	v_lshlrev_b64 v[36:37], 20, v[64:65]
	v_readlane_b32 s13, v252, 59
	v_mov_b32_e32 v67, v189
	v_mov_b32_e32 v35, v189
	v_lshl_add_u64 v[36:37], s[12:13], 0, v[36:37]
	v_lshl_add_u64 v[36:37], v[36:37], 0, v[66:67]
	v_lshl_add_u64 v[36:37], v[36:37], 0, v[34:35]
	s_waitcnt lgkmcnt(0)
	v_mul_f32_e32 v236, v28, v32
	v_mul_f32_e32 v237, v29, v32
	v_mul_f32_e32 v238, v30, v32
	v_mul_f32_e32 v239, v31, v32
	v_cmp_ne_u32_e32 vcc, 0, v232
	s_nop 1
	v_cndmask_b32_e32 v240, v237, v236, vcc
	v_cndmask_b32_e32 v241, v239, v238, vcc
	s_nop 1
	v_mov_b32_dpp v242, v240 quad_perm:[1,0,3,2] row_mask:0xf bank_mask:0xf
	v_mov_b32_dpp v243, v241 quad_perm:[1,0,3,2] row_mask:0xf bank_mask:0xf
	s_nop 1
	v_cndmask_b32_e32 v236, v236, v242, vcc
	v_cndmask_b32_e32 v237, v242, v237, vcc
	v_cndmask_b32_e32 v238, v238, v243, vcc
	v_cndmask_b32_e32 v239, v243, v239, vcc
	v_cmp_ne_u32_e32 vcc, 0, v233
	s_nop 1
	v_cndmask_b32_e32 v240, v238, v236, vcc
	v_cndmask_b32_e32 v241, v239, v237, vcc
	s_nop 1
	v_mov_b32_dpp v242, v240 quad_perm:[2,3,0,1] row_mask:0xf bank_mask:0xf
	v_mov_b32_dpp v243, v241 quad_perm:[2,3,0,1] row_mask:0xf bank_mask:0xf
	s_nop 1
	v_cndmask_b32_e32 v236, v236, v242, vcc
	v_cndmask_b32_e32 v238, v242, v238, vcc
	v_cndmask_b32_e32 v237, v237, v243, vcc
	v_cndmask_b32_e32 v239, v243, v239, vcc
	v_cvt_pk_bf16_f32 v244, v236, v237
	v_cvt_pk_bf16_f32 v245, v238, v239
	v_add_co_u32_e32 v234, vcc, 0xfff00000, v36
	s_nop 1
	v_addc_co_u32_e32 v235, vcc, -1, v37, vcc
	v_lshl_add_u64 v[234:235], v[234:235], 0, v[230:231]
	global_store_dwordx2 v[234:235], v[244:245], off
	s_nop 1
	s_andn2_saveexec_b64 s[2:3], s[2:3]
	s_cbranch_execz .LBB0_293

.LBB0_328:
	v_readlane_b32 s12, v252, 58
	v_lshlrev_b64 v[28:29], 20, v[64:65]
	v_readlane_b32 s13, v252, 59
	v_mov_b32_e32 v67, v189
	v_mov_b32_e32 v35, v189
	v_lshl_add_u64 v[28:29], s[12:13], 0, v[28:29]
	v_lshl_add_u64 v[28:29], v[28:29], 0, v[66:67]
	v_lshl_add_u64 v[28:29], v[28:29], 0, v[34:35]
	s_waitcnt lgkmcnt(0)
	v_mul_f32_e32 v236, v24, v32
	v_mul_f32_e32 v237, v25, v32
	v_mul_f32_e32 v238, v26, v32
	v_mul_f32_e32 v239, v27, v32
	v_cmp_ne_u32_e32 vcc, 0, v232
	s_nop 1
	v_cndmask_b32_e32 v240, v237, v236, vcc
	v_cndmask_b32_e32 v241, v239, v238, vcc
	s_nop 1
	v_mov_b32_dpp v242, v240 quad_perm:[1,0,3,2] row_mask:0xf bank_mask:0xf
	v_mov_b32_dpp v243, v241 quad_perm:[1,0,3,2] row_mask:0xf bank_mask:0xf
	s_nop 1
	v_cndmask_b32_e32 v236, v236, v242, vcc
	v_cndmask_b32_e32 v237, v242, v237, vcc
	v_cndmask_b32_e32 v238, v238, v243, vcc
	v_cndmask_b32_e32 v239, v243, v239, vcc
	v_cmp_ne_u32_e32 vcc, 0, v233
	s_nop 1
	v_cndmask_b32_e32 v240, v238, v236, vcc
	v_cndmask_b32_e32 v241, v239, v237, vcc
	s_nop 1
	v_mov_b32_dpp v242, v240 quad_perm:[2,3,0,1] row_mask:0xf bank_mask:0xf
	v_mov_b32_dpp v243, v241 quad_perm:[2,3,0,1] row_mask:0xf bank_mask:0xf
	s_nop 1
	v_cndmask_b32_e32 v236, v236, v242, vcc
	v_cndmask_b32_e32 v238, v242, v238, vcc
	v_cndmask_b32_e32 v237, v237, v243, vcc
	v_cndmask_b32_e32 v239, v243, v239, vcc
	v_cvt_pk_bf16_f32 v244, v236, v237
	v_cvt_pk_bf16_f32 v245, v238, v239
	v_add_co_u32_e32 v234, vcc, 0xfff40000, v28
	s_nop 1
	v_addc_co_u32_e32 v235, vcc, -1, v29, vcc
	v_lshl_add_u64 v[234:235], v[234:235], 0, v[230:231]
	global_store_dwordx2 v[234:235], v[244:245], off
	s_nop 1
	s_andn2_saveexec_b64 s[2:3], s[2:3]
	s_cbranch_execz .LBB0_295

.LBB0_330:
	v_readlane_b32 s12, v252, 58
	v_lshlrev_b64 v[24:25], 20, v[64:65]
	v_readlane_b32 s13, v252, 59
	v_mov_b32_e32 v67, v189
	v_mov_b32_e32 v35, v189
	v_lshl_add_u64 v[24:25], s[12:13], 0, v[24:25]
	v_lshl_add_u64 v[24:25], v[24:25], 0, v[66:67]
	v_lshl_add_u64 v[24:25], v[24:25], 0, v[34:35]
	s_waitcnt lgkmcnt(0)
	v_mul_f32_e32 v236, v20, v32
	v_mul_f32_e32 v237, v21, v32
	v_mul_f32_e32 v238, v22, v32
	v_mul_f32_e32 v239, v23, v32
	v_cmp_ne_u32_e32 vcc, 0, v232
	s_nop 1
	v_cndmask_b32_e32 v240, v237, v236, vcc
	v_cndmask_b32_e32 v241, v239, v238, vcc
	s_nop 1
	v_mov_b32_dpp v242, v240 quad_perm:[1,0,3,2] row_mask:0xf bank_mask:0xf
	v_mov_b32_dpp v243, v241 quad_perm:[1,0,3,2] row_mask:0xf bank_mask:0xf
	s_nop 1
	v_cndmask_b32_e32 v236, v236, v242, vcc
	v_cndmask_b32_e32 v237, v242, v237, vcc
	v_cndmask_b32_e32 v238, v238, v243, vcc
	v_cndmask_b32_e32 v239, v243, v239, vcc
	v_cmp_ne_u32_e32 vcc, 0, v233
	s_nop 1
	v_cndmask_b32_e32 v240, v238, v236, vcc
	v_cndmask_b32_e32 v241, v239, v237, vcc
	s_nop 1
	v_mov_b32_dpp v242, v240 quad_perm:[2,3,0,1] row_mask:0xf bank_mask:0xf
	v_mov_b32_dpp v243, v241 quad_perm:[2,3,0,1] row_mask:0xf bank_mask:0xf
	s_nop 1
	v_cndmask_b32_e32 v236, v236, v242, vcc
	v_cndmask_b32_e32 v238, v242, v238, vcc
	v_cndmask_b32_e32 v237, v237, v243, vcc
	v_cndmask_b32_e32 v239, v243, v239, vcc
	v_cvt_pk_bf16_f32 v244, v236, v237
	v_cvt_pk_bf16_f32 v245, v238, v239
	v_add_co_u32_e32 v234, vcc, 0xfff80000, v24
	s_nop 1
	v_addc_co_u32_e32 v235, vcc, -1, v25, vcc
	v_lshl_add_u64 v[234:235], v[234:235], 0, v[230:231]
	global_store_dwordx2 v[234:235], v[244:245], off
	s_nop 1
	s_andn2_saveexec_b64 s[2:3], s[2:3]
	s_cbranch_execz .LBB0_297

.LBB0_332:
	v_readlane_b32 s12, v252, 58
	v_lshlrev_b64 v[20:21], 20, v[64:65]
	v_readlane_b32 s13, v252, 59
	v_mov_b32_e32 v67, v189
	v_mov_b32_e32 v35, v189
	v_lshl_add_u64 v[20:21], s[12:13], 0, v[20:21]
	v_lshl_add_u64 v[20:21], v[20:21], 0, v[66:67]
	v_lshl_add_u64 v[20:21], v[20:21], 0, v[34:35]
	s_waitcnt lgkmcnt(0)
	v_mul_f32_e32 v236, v16, v32
	v_mul_f32_e32 v237, v17, v32
	v_mul_f32_e32 v238, v18, v32
	v_mul_f32_e32 v239, v19, v32
	v_cmp_ne_u32_e32 vcc, 0, v232
	s_nop 1
	v_cndmask_b32_e32 v240, v237, v236, vcc
	v_cndmask_b32_e32 v241, v239, v238, vcc
	s_nop 1
	v_mov_b32_dpp v242, v240 quad_perm:[1,0,3,2] row_mask:0xf bank_mask:0xf
	v_mov_b32_dpp v243, v241 quad_perm:[1,0,3,2] row_mask:0xf bank_mask:0xf
	s_nop 1
	v_cndmask_b32_e32 v236, v236, v242, vcc
	v_cndmask_b32_e32 v237, v242, v237, vcc
	v_cndmask_b32_e32 v238, v238, v243, vcc
	v_cndmask_b32_e32 v239, v243, v239, vcc
	v_cmp_ne_u32_e32 vcc, 0, v233
	s_nop 1
	v_cndmask_b32_e32 v240, v238, v236, vcc
	v_cndmask_b32_e32 v241, v239, v237, vcc
	s_nop 1
	v_mov_b32_dpp v242, v240 quad_perm:[2,3,0,1] row_mask:0xf bank_mask:0xf
	v_mov_b32_dpp v243, v241 quad_perm:[2,3,0,1] row_mask:0xf bank_mask:0xf
	s_nop 1
	v_cndmask_b32_e32 v236, v236, v242, vcc
	v_cndmask_b32_e32 v238, v242, v238, vcc
	v_cndmask_b32_e32 v237, v237, v243, vcc
	v_cndmask_b32_e32 v239, v243, v239, vcc
	v_cvt_pk_bf16_f32 v244, v236, v237
	v_cvt_pk_bf16_f32 v245, v238, v239
	v_add_co_u32_e32 v234, vcc, 0xfffc0000, v20
	s_nop 1
	v_addc_co_u32_e32 v235, vcc, -1, v21, vcc
	v_lshl_add_u64 v[234:235], v[234:235], 0, v[230:231]
	global_store_dwordx2 v[234:235], v[244:245], off
	s_nop 1
	s_andn2_saveexec_b64 s[2:3], s[2:3]
	s_cbranch_execnz .LBB0_299
	s_branch .LBB0_300
.LBB0_333:
	v_readlane_b32 s12, v252, 58
	v_lshlrev_b64 v[20:21], 20, v[64:65]
	v_readlane_b32 s13, v252, 59
	v_mov_b32_e32 v67, v189
	v_mov_b32_e32 v19, v189
	v_lshl_add_u64 v[20:21], s[12:13], 0, v[20:21]
	v_lshl_add_u64 v[20:21], v[20:21], 0, v[66:67]
	v_lshl_add_u64 v[20:21], v[20:21], 0, v[18:19]
	s_waitcnt lgkmcnt(0)
	v_mul_f32_e32 v236, v12, v16
	v_mul_f32_e32 v237, v13, v16
	v_mul_f32_e32 v238, v14, v16
	v_mul_f32_e32 v239, v15, v16
	v_cmp_ne_u32_e32 vcc, 0, v232
	s_nop 1
	v_cndmask_b32_e32 v240, v237, v236, vcc
	v_cndmask_b32_e32 v241, v239, v238, vcc
	s_nop 1
	v_mov_b32_dpp v242, v240 quad_perm:[1,0,3,2] row_mask:0xf bank_mask:0xf
	v_mov_b32_dpp v243, v241 quad_perm:[1,0,3,2] row_mask:0xf bank_mask:0xf
	s_nop 1
	v_cndmask_b32_e32 v236, v236, v242, vcc
	v_cndmask_b32_e32 v237, v242, v237, vcc
	v_cndmask_b32_e32 v238, v238, v243, vcc
	v_cndmask_b32_e32 v239, v243, v239, vcc
	v_cmp_ne_u32_e32 vcc, 0, v233
	s_nop 1
	v_cndmask_b32_e32 v240, v238, v236, vcc
	v_cndmask_b32_e32 v241, v239, v237, vcc
	s_nop 1
	v_mov_b32_dpp v242, v240 quad_perm:[2,3,0,1] row_mask:0xf bank_mask:0xf
	v_mov_b32_dpp v243, v241 quad_perm:[2,3,0,1] row_mask:0xf bank_mask:0xf
	s_nop 1
	v_cndmask_b32_e32 v236, v236, v242, vcc
	v_cndmask_b32_e32 v238, v242, v238, vcc
	v_cndmask_b32_e32 v237, v237, v243, vcc
	v_cndmask_b32_e32 v239, v243, v239, vcc
	v_cvt_pk_bf16_f32 v244, v236, v237
	v_cvt_pk_bf16_f32 v245, v238, v239
	v_add_co_u32_e32 v234, vcc, 0xfff00000, v20
	s_nop 1
	v_addc_co_u32_e32 v235, vcc, -1, v21, vcc
	v_lshl_add_u64 v[234:235], v[234:235], 0, v[230:231]
	global_store_dwordx2 v[234:235], v[244:245], off
	s_nop 1
	s_andn2_saveexec_b64 s[2:3], s[2:3]
	s_cbranch_execz .LBB0_302

.LBB0_335:
	v_readlane_b32 s12, v252, 58
	v_lshlrev_b64 v[12:13], 20, v[64:65]
	v_readlane_b32 s13, v252, 59
	v_mov_b32_e32 v67, v189
	v_mov_b32_e32 v19, v189
	v_lshl_add_u64 v[12:13], s[12:13], 0, v[12:13]
	v_lshl_add_u64 v[12:13], v[12:13], 0, v[66:67]
	v_lshl_add_u64 v[12:13], v[12:13], 0, v[18:19]
	s_waitcnt lgkmcnt(0)
	v_mul_f32_e32 v236, v8, v16
	v_mul_f32_e32 v237, v9, v16
	v_mul_f32_e32 v238, v10, v16
	v_mul_f32_e32 v239, v11, v16
	v_cmp_ne_u32_e32 vcc, 0, v232
	s_nop 1
	v_cndmask_b32_e32 v240, v237, v236, vcc
	v_cndmask_b32_e32 v241, v239, v238, vcc
	s_nop 1
	v_mov_b32_dpp v242, v240 quad_perm:[1,0,3,2] row_mask:0xf bank_mask:0xf
	v_mov_b32_dpp v243, v241 quad_perm:[1,0,3,2] row_mask:0xf bank_mask:0xf
	s_nop 1
	v_cndmask_b32_e32 v236, v236, v242, vcc
	v_cndmask_b32_e32 v237, v242, v237, vcc
	v_cndmask_b32_e32 v238, v238, v243, vcc
	v_cndmask_b32_e32 v239, v243, v239, vcc
	v_cmp_ne_u32_e32 vcc, 0, v233
	s_nop 1
	v_cndmask_b32_e32 v240, v238, v236, vcc
	v_cndmask_b32_e32 v241, v239, v237, vcc
	s_nop 1
	v_mov_b32_dpp v242, v240 quad_perm:[2,3,0,1] row_mask:0xf bank_mask:0xf
	v_mov_b32_dpp v243, v241 quad_perm:[2,3,0,1] row_mask:0xf bank_mask:0xf
	s_nop 1
	v_cndmask_b32_e32 v236, v236, v242, vcc
	v_cndmask_b32_e32 v238, v242, v238, vcc
	v_cndmask_b32_e32 v237, v237, v243, vcc
	v_cndmask_b32_e32 v239, v243, v239, vcc
	v_cvt_pk_bf16_f32 v244, v236, v237
	v_cvt_pk_bf16_f32 v245, v238, v239
	v_add_co_u32_e32 v234, vcc, 0xfff40000, v12
	s_nop 1
	v_addc_co_u32_e32 v235, vcc, -1, v13, vcc
	v_lshl_add_u64 v[234:235], v[234:235], 0, v[230:231]
	global_store_dwordx2 v[234:235], v[244:245], off
	s_nop 1
	s_andn2_saveexec_b64 s[2:3], s[2:3]
	s_cbranch_execz .LBB0_304

.LBB0_337:
	v_readlane_b32 s12, v252, 58
	v_lshlrev_b64 v[8:9], 20, v[64:65]
	v_readlane_b32 s13, v252, 59
	v_mov_b32_e32 v67, v189
	v_mov_b32_e32 v19, v189
	v_lshl_add_u64 v[8:9], s[12:13], 0, v[8:9]
	v_lshl_add_u64 v[8:9], v[8:9], 0, v[66:67]
	v_lshl_add_u64 v[8:9], v[8:9], 0, v[18:19]
	s_waitcnt lgkmcnt(0)
	v_mul_f32_e32 v236, v4, v16
	v_mul_f32_e32 v237, v5, v16
	v_mul_f32_e32 v238, v6, v16
	v_mul_f32_e32 v239, v7, v16
	v_cmp_ne_u32_e32 vcc, 0, v232
	s_nop 1
	v_cndmask_b32_e32 v240, v237, v236, vcc
	v_cndmask_b32_e32 v241, v239, v238, vcc
	s_nop 1
	v_mov_b32_dpp v242, v240 quad_perm:[1,0,3,2] row_mask:0xf bank_mask:0xf
	v_mov_b32_dpp v243, v241 quad_perm:[1,0,3,2] row_mask:0xf bank_mask:0xf
	s_nop 1
	v_cndmask_b32_e32 v236, v236, v242, vcc
	v_cndmask_b32_e32 v237, v242, v237, vcc
	v_cndmask_b32_e32 v238, v238, v243, vcc
	v_cndmask_b32_e32 v239, v243, v239, vcc
	v_cmp_ne_u32_e32 vcc, 0, v233
	s_nop 1
	v_cndmask_b32_e32 v240, v238, v236, vcc
	v_cndmask_b32_e32 v241, v239, v237, vcc
	s_nop 1
	v_mov_b32_dpp v242, v240 quad_perm:[2,3,0,1] row_mask:0xf bank_mask:0xf
	v_mov_b32_dpp v243, v241 quad_perm:[2,3,0,1] row_mask:0xf bank_mask:0xf
	s_nop 1
	v_cndmask_b32_e32 v236, v236, v242, vcc
	v_cndmask_b32_e32 v238, v242, v238, vcc
	v_cndmask_b32_e32 v237, v237, v243, vcc
	v_cndmask_b32_e32 v239, v243, v239, vcc
	v_cvt_pk_bf16_f32 v244, v236, v237
	v_cvt_pk_bf16_f32 v245, v238, v239
	v_add_co_u32_e32 v234, vcc, 0xfff80000, v8
	s_nop 1
	v_addc_co_u32_e32 v235, vcc, -1, v9, vcc
	v_lshl_add_u64 v[234:235], v[234:235], 0, v[230:231]
	global_store_dwordx2 v[234:235], v[244:245], off
	s_nop 1
	s_andn2_saveexec_b64 s[2:3], s[2:3]
	s_cbranch_execz .LBB0_306

.LBB0_339:
	v_readlane_b32 s4, v252, 58
	v_lshlrev_b64 v[4:5], 20, v[64:65]
	v_readlane_b32 s5, v252, 59
	v_mov_b32_e32 v67, v189
	v_mov_b32_e32 v19, v189
	v_lshl_add_u64 v[4:5], s[4:5], 0, v[4:5]
	v_lshl_add_u64 v[4:5], v[4:5], 0, v[66:67]
	v_lshl_add_u64 v[4:5], v[4:5], 0, v[18:19]
	s_waitcnt lgkmcnt(0)
	v_mul_f32_e32 v236, v0, v16
	v_mul_f32_e32 v237, v1, v16
	v_mul_f32_e32 v238, v2, v16
	v_mul_f32_e32 v239, v3, v16
	v_cmp_ne_u32_e32 vcc, 0, v232
	s_nop 1
	v_cndmask_b32_e32 v240, v237, v236, vcc
	v_cndmask_b32_e32 v241, v239, v238, vcc
	s_nop 1
	v_mov_b32_dpp v242, v240 quad_perm:[1,0,3,2] row_mask:0xf bank_mask:0xf
	v_mov_b32_dpp v243, v241 quad_perm:[1,0,3,2] row_mask:0xf bank_mask:0xf
	s_nop 1
	v_cndmask_b32_e32 v236, v236, v242, vcc
	v_cndmask_b32_e32 v237, v242, v237, vcc
	v_cndmask_b32_e32 v238, v238, v243, vcc
	v_cndmask_b32_e32 v239, v243, v239, vcc
	v_cmp_ne_u32_e32 vcc, 0, v233
	s_nop 1
	v_cndmask_b32_e32 v240, v238, v236, vcc
	v_cndmask_b32_e32 v241, v239, v237, vcc
	s_nop 1
	v_mov_b32_dpp v242, v240 quad_perm:[2,3,0,1] row_mask:0xf bank_mask:0xf
	v_mov_b32_dpp v243, v241 quad_perm:[2,3,0,1] row_mask:0xf bank_mask:0xf
	s_nop 1
	v_cndmask_b32_e32 v236, v236, v242, vcc
	v_cndmask_b32_e32 v238, v242, v238, vcc
	v_cndmask_b32_e32 v237, v237, v243, vcc
	v_cndmask_b32_e32 v239, v243, v239, vcc
	v_cvt_pk_bf16_f32 v244, v236, v237
	v_cvt_pk_bf16_f32 v245, v238, v239
	v_add_co_u32_e32 v234, vcc, 0xfffc0000, v4
	s_nop 1
	v_addc_co_u32_e32 v235, vcc, -1, v5, vcc
	v_lshl_add_u64 v[234:235], v[234:235], 0, v[230:231]
	global_store_dwordx2 v[234:235], v[244:245], off
	s_nop 1
	s_andn2_saveexec_b64 s[2:3], s[2:3]
	s_cbranch_execnz .LBB0_308
	s_branch .LBB0_309
